# weight conversion (w_in tiles): the 8 predicated f32 source loads per tile were serialised by vmcnt(0) after each; now issued together with one wait
# speedup vs baseline: 1.0163x; 1.0163x over previous
; DEVI void conv_tile(unsigned char* smem, const float* src, int ldsrc, int K, bf16_t* dst, int mode, int ntile, int ktile) {
;     ...
; #pragma unroll
;     for (int i = 0; i < 8; ++i) {
;         const int kk = ty + 8 * i;
;         tile[kk * 65 + tx] = sc >= 0 ? src[(size_t)(k0 + kk) * ldsrc + sc] : 0.0f;
;     }
;     __syncthreads();
;     const int nr = tid >> 3, ks = (tid & 7) * 8;
;     float v[8];
; #pragma unroll
;     for (int j = 0; j < 8; ++j) v[j] = tile[(ks + j) * 65 + nr];
;     u32x4 w; w.x = cvt_pk_bf16(v[0], v[1]); w.y = cvt_pk_bf16(v[2], v[3]); w.z = cvt_pk_bf16(v[4], v[5]); w.w = cvt_pk_bf16(v[6], v[7]);
;     *(u32x4*)(dst + (size_t)(n0 + nr) * K + k0 + ks) = w;
;     __syncthreads();
.LBB0_37:
	s_or_b64 exec, exec, s[4:5]
	s_waitcnt vmcnt(0)
	ds_write_b32 v2, v220
	ds_write_b32 v2, v221 offset:2080
	ds_write_b32 v2, v222 offset:4160
	ds_write_b32 v2, v223 offset:6240
	ds_write_b32 v2, v224 offset:8320
	ds_write_b32 v2, v225 offset:10400
	ds_write_b32 v2, v226 offset:12480
	ds_write_b32 v2, v227 offset:14560
	v_ashrrev_i32_e32 v2, 3, v1
	v_lshlrev_b32_e32 v1, 3, v1
	v_and_b32_e32 v1, 56, v1
	v_lshlrev_b32_e32 v4, 2, v2
	v_mul_u32_u24_e32 v5, 0x104, v1
	v_add3_u32 v8, 0, v4, v5
	s_waitcnt lgkmcnt(0)
	s_barrier
	ds_read2_b32 v[4:5], v8 offset1:65
	ds_read2_b32 v[6:7], v8 offset0:130 offset1:195
	v_add_u32_e32 v10, 0x400, v8
	ds_read2_b32 v[8:9], v10 offset0:4 offset1:69
	ds_read2_b32 v[10:11], v10 offset0:134 offset1:199
	s_lshl_b32 s2, s2, 11
	s_waitcnt lgkmcnt(3)
	v_cvt_pk_bf16_f32 v4, v4, v5
	s_waitcnt lgkmcnt(2)
	v_cvt_pk_bf16_f32 v5, v6, v7
	s_waitcnt lgkmcnt(1)
	v_cvt_pk_bf16_f32 v6, v8, v9
	v_add_u32_e32 v8, s0, v2
	v_ashrrev_i32_e32 v9, 31, v8
	s_sub_i32 s4, s3, s2
	v_lshlrev_b64 v[8:9], 12, v[8:9]
	v_lshl_add_u64 v[8:9], s[88:89], 0, v[8:9]
	s_ashr_i32 s5, s4, 31
	v_lshl_add_u64 v[8:9], s[4:5], 1, v[8:9]
	v_lshlrev_b32_e32 v2, 1, v1
	s_waitcnt lgkmcnt(0)
	v_cvt_pk_bf16_f32 v7, v10, v11
	v_lshl_add_u64 v[8:9], v[8:9], 0, v[2:3]
	global_store_dwordx4 v[8:9], v[4:7], off
	s_barrier

; DEVI int srccol_ffn(int n) { return ((n >> 7) & 1) * FFN_H + (n >> 8) * 128 + (n & 127); }
; DEVI void conv_tile(unsigned char* smem, const float* src, int ldsrc, int K, bf16_t* dst, int mode, int ntile, int ktile) {
;     ...
;     const int n = n0 + tx;
;     const int sc = mode == 0 ? srccol_win(n) : (mode == 1 ? srccol_ffn(n) : n);
; #pragma unroll
;     for (int i = 0; i < 8; ++i) {
;         const int kk = ty + 8 * i;
;         tile[kk * 65 + tx] = sc >= 0 ? src[(size_t)(k0 + kk) * ldsrc + sc] : 0.0f;
;     }
.LBB0_80:
	s_or_b64 exec, exec, s[4:5]
	v_readlane_b32 s36, v252, 6
	v_readlane_b32 s48, v252, 18
	v_readlane_b32 s49, v252, 19
	v_ashrrev_i32_e32 v6, 6, v1
	v_cmp_lt_i32_e32 vcc, -1, v2
	v_lshl_add_u64 v[4:5], v[2:3], 2, s[48:49]
	v_mov_b32_e32 v8, 0
	v_mov_b32_e32 v9, 0
	v_readlane_b32 s37, v252, 7
	v_readlane_b32 s38, v252, 8
	v_readlane_b32 s39, v252, 9
	v_readlane_b32 s40, v252, 10
	v_readlane_b32 s41, v252, 11
	v_readlane_b32 s42, v252, 12
	v_readlane_b32 s43, v252, 13
	v_readlane_b32 s44, v252, 14
	v_readlane_b32 s45, v252, 15
	v_readlane_b32 s46, v252, 16
	v_readlane_b32 s47, v252, 17
	v_readlane_b32 s50, v252, 20
	v_readlane_b32 s51, v252, 21
	v_mov_b32_e32 v220, 0
	s_and_saveexec_b64 s[4:5], vcc
	s_cbranch_execz .LBB0_82
	s_lshl_b32 s6, s2, 11
	v_subrev_u32_e32 v2, s6, v6
	v_add_u32_e32 v2, s3, v2
	v_mad_i64_i32 v[10:11], s[6:7], v2, s17, v[4:5]
	global_load_dword v220, v[10:11], off
.LBB0_82:
	s_or_b64 exec, exec, s[4:5]
	v_lshl_add_u32 v2, v7, 2, 0
	v_mul_lo_u32 v7, v6, s15
	v_add_u32_e32 v2, v2, v7
	v_mov_b32_e32 v221, 0
	s_and_saveexec_b64 s[4:5], vcc
	s_cbranch_execz .LBB0_84
	s_lshl_b32 s6, s2, 11
	v_subrev_u32_e32 v7, s6, v6
	v_add3_u32 v7, s3, v7, 8
	v_mad_i64_i32 v[8:9], s[6:7], v7, s17, v[4:5]
	global_load_dword v221, v[8:9], off
.LBB0_84:
	s_or_b64 exec, exec, s[4:5]
	v_mov_b32_e32 v7, 0
	v_mov_b32_e32 v8, 0
	v_mov_b32_e32 v222, 0
	s_and_saveexec_b64 s[4:5], vcc
	s_cbranch_execz .LBB0_86
	s_lshl_b32 s6, s2, 11
	v_subrev_u32_e32 v8, s6, v6
	v_add3_u32 v8, s3, v8, 16
	v_mad_i64_i32 v[8:9], s[6:7], v8, s17, v[4:5]
	global_load_dword v222, v[8:9], off
.LBB0_86:
	s_or_b64 exec, exec, s[4:5]
	v_mov_b32_e32 v223, 0
	s_and_saveexec_b64 s[4:5], vcc
	s_cbranch_execz .LBB0_88
	s_lshl_b32 s6, s2, 11
	v_subrev_u32_e32 v7, s6, v6
	v_add3_u32 v7, s3, v7, 24
	v_mad_i64_i32 v[8:9], s[6:7], v7, s17, v[4:5]
	global_load_dword v223, v[8:9], off
.LBB0_88:
	s_or_b64 exec, exec, s[4:5]
	v_mov_b32_e32 v7, 0
	v_mov_b32_e32 v8, 0
	v_mov_b32_e32 v224, 0
	s_and_saveexec_b64 s[4:5], vcc
	s_cbranch_execz .LBB0_90
	s_lshl_b32 s6, s2, 11
	v_subrev_u32_e32 v8, s6, v6
	v_add3_u32 v8, s3, v8, 32
	v_mad_i64_i32 v[8:9], s[6:7], v8, s17, v[4:5]
	global_load_dword v224, v[8:9], off
.LBB0_90:
	s_or_b64 exec, exec, s[4:5]
	v_mov_b32_e32 v225, 0
	s_and_saveexec_b64 s[4:5], vcc
	s_cbranch_execz .LBB0_92
	s_lshl_b32 s6, s2, 11
	v_subrev_u32_e32 v7, s6, v6
	v_add3_u32 v7, s3, v7, 40
	v_mad_i64_i32 v[8:9], s[6:7], v7, s17, v[4:5]
	global_load_dword v225, v[8:9], off
.LBB0_92:
	s_or_b64 exec, exec, s[4:5]
	v_mov_b32_e32 v7, 0
	v_mov_b32_e32 v8, 0
	v_mov_b32_e32 v226, 0
	s_and_saveexec_b64 s[4:5], vcc
	s_cbranch_execz .LBB0_94
	s_lshl_b32 s6, s2, 11
	v_subrev_u32_e32 v8, s6, v6
	v_add3_u32 v8, s3, v8, 48
	v_mad_i64_i32 v[8:9], s[6:7], v8, s17, v[4:5]
	global_load_dword v226, v[8:9], off
.LBB0_94:
	s_or_b64 exec, exec, s[4:5]
	v_mov_b32_e32 v227, 0
	s_and_saveexec_b64 s[4:5], vcc
	s_cbranch_execz .LBB0_37
	s_lshl_b32 s6, s2, 11
	v_subrev_u32_e32 v6, s6, v6
	v_add3_u32 v6, s3, v6, 56
	v_mad_i64_i32 v[4:5], s[6:7], v6, s17, v[4:5]
	global_load_dword v227, v[4:5], off
	s_branch .LBB0_37

; DEVI void conv_tile(unsigned char* smem, const float* src, int ldsrc, int K, bf16_t* dst, int mode, int ntile, int ktile) {
;     ...
;         tile[kk * 65 + tx] = sc >= 0 ? src[(size_t)(k0 + kk) * ldsrc + sc] : 0.0f;
;     }
;     __syncthreads();
;     const int nr = tid >> 3, ks = (tid & 7) * 8;
;     float v[8];
; #pragma unroll
;     for (int j = 0; j < 8; ++j) v[j] = tile[(ks + j) * 65 + nr];
;     u32x4 w; w.x = cvt_pk_bf16(v[0], v[1]); w.y = cvt_pk_bf16(v[2], v[3]); w.z = cvt_pk_bf16(v[4], v[5]); w.w = cvt_pk_bf16(v[6], v[7]);
;     *(u32x4*)(dst + (size_t)(n0 + nr) * K + k0 + ks) = w;
;     __syncthreads();
.LBB0_134:
	s_or_b64 exec, exec, s[0:1]
	v_lshlrev_b32_e32 v0, 3, v2
	v_ashrrev_i32_e32 v8, 3, v2
	v_and_b32_e32 v9, 56, v0
	v_lshlrev_b32_e32 v0, 2, v8
	v_mul_u32_u24_e32 v1, 0x104, v9
	s_waitcnt vmcnt(0)
	ds_write_b32 v4, v220
	ds_write_b32 v4, v221 offset:2080
	ds_write_b32 v4, v222 offset:4160
	ds_write_b32 v4, v223 offset:6240
	ds_write_b32 v4, v224 offset:8320
	ds_write_b32 v4, v225 offset:10400
	ds_write_b32 v4, v226 offset:12480
	ds_write_b32 v4, v227 offset:14560
	v_add3_u32 v4, 0, v0, v1
	s_waitcnt lgkmcnt(0)
	s_barrier
	ds_read2_b32 v[0:1], v4 offset1:65
	ds_read2_b32 v[2:3], v4 offset0:130 offset1:195
	v_add_u32_e32 v6, 0x400, v4
	ds_read2_b32 v[4:5], v6 offset0:4 offset1:69
	ds_read2_b32 v[6:7], v6 offset0:134 offset1:199
	s_lshl_b32 s0, s3, 11
	s_waitcnt lgkmcnt(3)
	v_cvt_pk_bf16_f32 v0, v0, v1
	s_waitcnt lgkmcnt(2)
	v_cvt_pk_bf16_f32 v1, v2, v3
	s_waitcnt lgkmcnt(1)
	v_cvt_pk_bf16_f32 v2, v4, v5
	v_add_u32_e32 v4, s2, v8
	v_ashrrev_i32_e32 v5, 31, v4
	s_sub_i32 s0, s14, s0
	v_lshlrev_b64 v[4:5], 12, v[4:5]
	v_lshl_add_u64 v[4:5], s[88:89], 0, v[4:5]
	s_ashr_i32 s1, s0, 31
	v_lshl_add_u64 v[4:5], s[0:1], 1, v[4:5]
	v_lshlrev_b32_e32 v148, 1, v9
	s_waitcnt lgkmcnt(0)
	v_cvt_pk_bf16_f32 v3, v6, v7
	v_lshl_add_u64 v[4:5], v[4:5], 0, v[148:149]
	global_store_dwordx4 v[4:5], v[0:3], off
	s_barrier

; DEVI int srccol_ffn(int n) { return ((n >> 7) & 1) * FFN_H + (n >> 8) * 128 + (n & 127); }
; DEVI void conv_tile(unsigned char* smem, const float* src, int ldsrc, int K, bf16_t* dst, int mode, int ntile, int ktile) {
;     ...
;     const int n = n0 + tx;
;     const int sc = mode == 0 ? srccol_win(n) : (mode == 1 ? srccol_ffn(n) : n);
; #pragma unroll
;     for (int i = 0; i < 8; ++i) {
;         const int kk = ty + 8 * i;
;         tile[kk * 65 + tx] = sc >= 0 ? src[(size_t)(k0 + kk) * ldsrc + sc] : 0.0f;
;     }
.LBB0_177:
	s_or_b64 exec, exec, s[0:1]
	v_readlane_b32 s0, v254, 10
	v_readlane_b32 s1, v254, 11
	v_ashrrev_i32_e32 v3, 6, v2
	v_cmp_lt_i32_e32 vcc, -1, v148
	v_lshl_add_u64 v[0:1], v[148:149], 2, s[0:1]
	v_mov_b32_e32 v5, 0
	v_mov_b32_e32 v6, 0
	v_mov_b32_e32 v220, 0
	s_and_saveexec_b64 s[0:1], vcc
	s_cbranch_execz .LBB0_179
	s_lshl_b32 s6, s3, 11
	v_subrev_u32_e32 v6, s6, v3
	v_add_u32_e32 v6, s14, v6
	s_mov_b32 s6, 0xf340
	v_mad_i64_i32 v[6:7], s[6:7], v6, s6, v[0:1]
	global_load_dword v220, v[6:7], off
.LBB0_179:
	s_or_b64 exec, exec, s[0:1]
	v_lshl_add_u32 v4, v4, 2, 0
	v_mul_lo_u32 v7, v3, s86
	v_add_u32_e32 v4, v4, v7
	v_mov_b32_e32 v221, 0
	s_and_saveexec_b64 s[0:1], vcc
	s_cbranch_execz .LBB0_181
	s_lshl_b32 s6, s3, 11
	v_subrev_u32_e32 v5, s6, v3
	v_add3_u32 v5, s14, v5, 8
	s_mov_b32 s6, 0xf340
	v_mad_i64_i32 v[6:7], s[6:7], v5, s6, v[0:1]
	global_load_dword v221, v[6:7], off
.LBB0_181:
	s_or_b64 exec, exec, s[0:1]
	v_mov_b32_e32 v5, 0
	v_mov_b32_e32 v6, 0
	v_mov_b32_e32 v222, 0
	s_and_saveexec_b64 s[0:1], vcc
	s_cbranch_execz .LBB0_183
	s_lshl_b32 s6, s3, 11
	v_subrev_u32_e32 v6, s6, v3
	v_add3_u32 v6, s14, v6, 16
	s_mov_b32 s6, 0xf340
	v_mad_i64_i32 v[6:7], s[6:7], v6, s6, v[0:1]
	global_load_dword v222, v[6:7], off
.LBB0_183:
	s_or_b64 exec, exec, s[0:1]
	v_mov_b32_e32 v223, 0
	s_and_saveexec_b64 s[0:1], vcc
	s_cbranch_execz .LBB0_185
	s_lshl_b32 s6, s3, 11
	v_subrev_u32_e32 v5, s6, v3
	v_add3_u32 v5, s14, v5, 24
	s_mov_b32 s6, 0xf340
	v_mad_i64_i32 v[6:7], s[6:7], v5, s6, v[0:1]
	global_load_dword v223, v[6:7], off
.LBB0_185:
	s_or_b64 exec, exec, s[0:1]
	v_mov_b32_e32 v5, 0
	v_mov_b32_e32 v6, 0
	v_mov_b32_e32 v224, 0
	s_and_saveexec_b64 s[0:1], vcc
	s_cbranch_execz .LBB0_187
	s_lshl_b32 s6, s3, 11
	v_subrev_u32_e32 v6, s6, v3
	v_add3_u32 v6, s14, v6, 32
	s_mov_b32 s6, 0xf340
	v_mad_i64_i32 v[6:7], s[6:7], v6, s6, v[0:1]
	global_load_dword v224, v[6:7], off
.LBB0_187:
	s_or_b64 exec, exec, s[0:1]
	v_mov_b32_e32 v225, 0
	s_and_saveexec_b64 s[0:1], vcc
	s_cbranch_execz .LBB0_189
	s_lshl_b32 s6, s3, 11
	v_subrev_u32_e32 v5, s6, v3
	v_add3_u32 v5, s14, v5, 40
	s_mov_b32 s6, 0xf340
	v_mad_i64_i32 v[6:7], s[6:7], v5, s6, v[0:1]
	global_load_dword v225, v[6:7], off
.LBB0_189:
	s_or_b64 exec, exec, s[0:1]
	v_mov_b32_e32 v5, 0
	v_mov_b32_e32 v6, 0
	v_mov_b32_e32 v226, 0
	s_and_saveexec_b64 s[0:1], vcc
	s_cbranch_execz .LBB0_191
	s_lshl_b32 s6, s3, 11
	v_subrev_u32_e32 v6, s6, v3
	v_add3_u32 v6, s14, v6, 48
	s_mov_b32 s6, 0xf340
	v_mad_i64_i32 v[6:7], s[6:7], v6, s6, v[0:1]
	global_load_dword v226, v[6:7], off
.LBB0_191:
	s_or_b64 exec, exec, s[0:1]
	v_mov_b32_e32 v227, 0
	s_and_saveexec_b64 s[0:1], vcc
	s_cbranch_execz .LBB0_134
	s_lshl_b32 s6, s3, 11
	v_subrev_u32_e32 v3, s6, v3
	v_add3_u32 v3, s14, v3, 56
	s_mov_b32 s6, 0xf340
	v_mad_i64_i32 v[0:1], s[6:7], v3, s6, v[0:1]
	global_load_dword v227, v[0:1], off
	s_branch .LBB0_134
